# ssd3 output epilogue: 8 rmsnorm weight vectors loaded once up front (no per-store vmcnt(0) chain)
# speedup vs baseline: 1.0154x; 1.0061x over previous
.LBB0_129:
	s_or_b64 exec, exec, s[2:3]
	v_readlane_b32 s2, v255, 4
	v_readlane_b32 s3, v255, 5
	s_andn2_b64 vcc, exec, s[2:3]
	s_waitcnt lgkmcnt(0)
	s_barrier
	s_cbranch_vccnz .LBB0_34
	v_add_u32_e32 v69, 0x8800, v186
	ds_read2_b32 v[72:73], v69 offset1:32
	ds_read2_b32 v[74:75], v69 offset0:128 offset1:160
	s_mov_b32 s2, 0x800000
	v_readlane_b32 s3, v255, 20
	v_lshlrev_b32_e32 v82, 6, v162
	s_waitcnt lgkmcnt(0)
	v_add_f32_e32 v69, v72, v74
	v_add_u32_e32 v72, 0x8c00, v186
	ds_read2_b32 v[76:77], v72 offset1:32
	ds_read2_b32 v[78:79], v72 offset0:128 offset1:160
	v_add_u32_e32 v16, s3, v169
	v_ashrrev_i32_e32 v17, 31, v16
	v_lshl_add_u64 v[16:17], s[0:1], 0, v[16:17]
	s_waitcnt lgkmcnt(1)
	v_add_f32_e32 v69, v69, v76
	s_waitcnt lgkmcnt(0)
	v_add_f32_e32 v69, v69, v78
	v_fmamk_f32 v69, v69, 0x3b800000, v178
	v_cmp_gt_f32_e32 vcc, s2, v69
	v_mul_f32_e32 v72, 0x4b800000, v69
	v_lshlrev_b64 v[16:17], 12, v[16:17]
	v_cndmask_b32_e32 v69, v69, v72, vcc
	v_rsq_f32_e32 v69, v69
	v_lshl_add_u64 v[16:17], v[66:67], 0, v[16:17]
	v_mul_f32_e32 v72, 0x45800000, v69
	v_cndmask_b32_e32 v72, v69, v72, vcc
	v_mov_b32_e32 v69, v1
	v_lshl_add_u64 v[80:81], v[16:17], 0, v[68:69]
	v_lshlrev_b32_e32 v16, 2, v82
	v_mov_b32_e32 v17, v1
	v_lshl_add_u64 v[16:17], v[158:159], 0, v[16:17]
	global_load_dwordx4 v[200:203], v[16:17], off
	global_load_dwordx4 v[204:207], v[16:17], off offset:32
	global_load_dwordx4 v[208:211], v[16:17], off offset:64
	global_load_dwordx4 v[212:215], v[16:17], off offset:96
	global_load_dwordx4 v[222:225], v[16:17], off offset:128
	global_load_dwordx4 v[226:229], v[16:17], off offset:160
	global_load_dwordx4 v[130:133], v[16:17], off offset:192
	global_load_dwordx4 v[134:137], v[16:17], off offset:224
	v_pk_mul_f32 v[70:71], v[70:71], v[72:73] op_sel_hi:[1,0]
	v_pk_mul_f32 v[50:51], v[50:51], v[72:73] op_sel_hi:[1,0]
	v_pk_mul_f32 v[52:53], v[52:53], v[72:73] op_sel_hi:[1,0]
	v_pk_mul_f32 v[34:35], v[34:35], v[72:73] op_sel_hi:[1,0]
	v_pk_mul_f32 v[36:37], v[36:37], v[72:73] op_sel_hi:[1,0]
	s_waitcnt vmcnt(0)
	v_mov_b32_e32 v82, v200
	v_mov_b32_e32 v83, v201
	v_mov_b32_e32 v84, v202
	v_mov_b32_e32 v85, v203
	v_pk_mul_f32 v[70:71], v[82:83], v[70:71]
	v_pk_mul_f32 v[50:51], v[84:85], v[50:51]
	v_cvt_pk_bf16_f32 v70, v70, v71
	v_cvt_pk_bf16_f32 v71, v50, v51
	global_store_dwordx2 v[80:81], v[70:71], off
	v_pk_mul_f32 v[50:51], v[54:55], v[72:73] op_sel_hi:[1,0]
	v_pk_mul_f32 v[54:55], v[58:59], v[72:73] op_sel_hi:[1,0]
	v_mov_b32_e32 v82, v204
	v_mov_b32_e32 v83, v205
	v_mov_b32_e32 v84, v206
	v_mov_b32_e32 v85, v207
	v_pk_mul_f32 v[50:51], v[82:83], v[50:51]
	v_pk_mul_f32 v[52:53], v[84:85], v[52:53]
	v_cvt_pk_bf16_f32 v50, v50, v51
	v_cvt_pk_bf16_f32 v51, v52, v53
	global_store_dwordx2 v[80:81], v[50:51], off offset:16
	v_mov_b32_e32 v50, v208
	v_mov_b32_e32 v51, v209
	v_mov_b32_e32 v52, v210
	v_mov_b32_e32 v53, v211
	v_pk_mul_f32 v[50:51], v[54:55], v[50:51]
	v_pk_mul_f32 v[54:55], v[56:57], v[72:73] op_sel_hi:[1,0]
	v_cvt_pk_bf16_f32 v50, v50, v51
	v_pk_mul_f32 v[52:53], v[54:55], v[52:53]
	v_pk_mul_f32 v[54:55], v[62:63], v[72:73] op_sel_hi:[1,0]
	v_cvt_pk_bf16_f32 v51, v52, v53
	global_store_dwordx2 v[80:81], v[50:51], off offset:32
	v_mov_b32_e32 v50, v212
	v_mov_b32_e32 v51, v213
	v_mov_b32_e32 v52, v214
	v_mov_b32_e32 v53, v215
	v_pk_mul_f32 v[50:51], v[54:55], v[50:51]
	v_pk_mul_f32 v[54:55], v[60:61], v[72:73] op_sel_hi:[1,0]
	v_cvt_pk_bf16_f32 v50, v50, v51
	v_pk_mul_f32 v[52:53], v[54:55], v[52:53]
	v_pk_mul_f32 v[54:55], v[64:65], v[72:73] op_sel_hi:[1,0]
	v_cvt_pk_bf16_f32 v51, v52, v53
	global_store_dwordx2 v[80:81], v[50:51], off offset:48
	v_mov_b32_e32 v50, v222
	v_mov_b32_e32 v51, v223
	v_mov_b32_e32 v52, v224
	v_mov_b32_e32 v53, v225
	v_pk_mul_f32 v[50:51], v[54:55], v[50:51]
	v_pk_mul_f32 v[34:35], v[34:35], v[52:53]
	v_cvt_pk_bf16_f32 v50, v50, v51
	v_cvt_pk_bf16_f32 v51, v34, v35
	global_store_dwordx2 v[80:81], v[50:51], off offset:64
	v_pk_mul_f32 v[34:35], v[38:39], v[72:73] op_sel_hi:[1,0]
	v_pk_mul_f32 v[38:39], v[42:43], v[72:73] op_sel_hi:[1,0]
	v_mov_b32_e32 v50, v226
	v_mov_b32_e32 v51, v227
	v_mov_b32_e32 v52, v228
	v_mov_b32_e32 v53, v229
	v_pk_mul_f32 v[34:35], v[34:35], v[50:51]
	v_pk_mul_f32 v[36:37], v[36:37], v[52:53]
	v_cvt_pk_bf16_f32 v34, v34, v35
	v_cvt_pk_bf16_f32 v35, v36, v37
	global_store_dwordx2 v[80:81], v[34:35], off offset:80
	v_mov_b32_e32 v34, v130
	v_mov_b32_e32 v35, v131
	v_mov_b32_e32 v36, v132
	v_mov_b32_e32 v37, v133
	v_pk_mul_f32 v[34:35], v[38:39], v[34:35]
	v_pk_mul_f32 v[38:39], v[40:41], v[72:73] op_sel_hi:[1,0]
	v_cvt_pk_bf16_f32 v34, v34, v35
	v_pk_mul_f32 v[36:37], v[38:39], v[36:37]
	v_pk_mul_f32 v[38:39], v[44:45], v[72:73] op_sel_hi:[1,0]
	v_cvt_pk_bf16_f32 v35, v36, v37
	global_store_dwordx2 v[80:81], v[34:35], off offset:96
	v_mov_b32_e32 v34, v134
	v_mov_b32_e32 v35, v135
	v_mov_b32_e32 v36, v136
	v_mov_b32_e32 v37, v137
	v_pk_mul_f32 v[34:35], v[38:39], v[34:35]
	v_pk_mul_f32 v[38:39], v[46:47], v[72:73] op_sel_hi:[1,0]
	v_cvt_pk_bf16_f32 v34, v34, v35
	v_pk_mul_f32 v[36:37], v[38:39], v[36:37]
	s_nop 0
	v_cvt_pk_bf16_f32 v35, v36, v37
	global_store_dwordx2 v[80:81], v[34:35], off offset:112
	v_add_f32_e32 v36, v73, v75
	v_add_f32_e32 v36, v36, v77
	v_add_f32_e32 v36, v36, v79
	v_fmamk_f32 v36, v36, 0x3b800000, v178
	v_cmp_gt_f32_e32 vcc, s2, v36
	v_mul_f32_e32 v37, 0x4b800000, v36
	v_add_u32_e32 v34, s3, v180
	v_cndmask_b32_e32 v36, v36, v37, vcc
	v_rsq_f32_e32 v36, v36
	v_ashrrev_i32_e32 v35, 31, v34
	v_lshl_add_u64 v[34:35], s[0:1], 0, v[34:35]
	v_lshlrev_b64 v[34:35], 12, v[34:35]
	v_mul_f32_e32 v37, 0x45800000, v36
	v_cndmask_b32_e32 v36, v36, v37, vcc
	v_pk_mul_f32 v[42:43], v[48:49], v[36:37] op_sel_hi:[1,0]
	v_pk_mul_f32 v[18:19], v[18:19], v[36:37] op_sel_hi:[1,0]
	v_lshl_add_u64 v[34:35], v[66:67], 0, v[34:35]
	v_lshl_add_u64 v[34:35], v[34:35], 0, v[68:69]
	v_pk_mul_f32 v[20:21], v[20:21], v[36:37] op_sel_hi:[1,0]
	v_pk_mul_f32 v[2:3], v[2:3], v[36:37] op_sel_hi:[1,0]
	v_pk_mul_f32 v[4:5], v[4:5], v[36:37] op_sel_hi:[1,0]
	v_mov_b32_e32 v38, v200
	v_mov_b32_e32 v39, v201
	v_mov_b32_e32 v40, v202
	v_mov_b32_e32 v41, v203
	v_pk_mul_f32 v[38:39], v[38:39], v[42:43]
	v_pk_mul_f32 v[18:19], v[40:41], v[18:19]
	v_cvt_pk_bf16_f32 v38, v38, v39
	v_cvt_pk_bf16_f32 v39, v18, v19
	global_store_dwordx2 v[34:35], v[38:39], off
	v_pk_mul_f32 v[18:19], v[22:23], v[36:37] op_sel_hi:[1,0]
	v_pk_mul_f32 v[22:23], v[26:27], v[36:37] op_sel_hi:[1,0]
	v_mov_b32_e32 v38, v204
	v_mov_b32_e32 v39, v205
	v_mov_b32_e32 v40, v206
	v_mov_b32_e32 v41, v207
	v_pk_mul_f32 v[18:19], v[38:39], v[18:19]
	v_pk_mul_f32 v[20:21], v[40:41], v[20:21]
	v_cvt_pk_bf16_f32 v18, v18, v19
	v_cvt_pk_bf16_f32 v19, v20, v21
	global_store_dwordx2 v[34:35], v[18:19], off offset:16
	v_mov_b32_e32 v18, v208
	v_mov_b32_e32 v19, v209
	v_mov_b32_e32 v20, v210
	v_mov_b32_e32 v21, v211
	v_pk_mul_f32 v[18:19], v[22:23], v[18:19]
	v_pk_mul_f32 v[22:23], v[24:25], v[36:37] op_sel_hi:[1,0]
	v_cvt_pk_bf16_f32 v18, v18, v19
	v_pk_mul_f32 v[20:21], v[22:23], v[20:21]
	v_pk_mul_f32 v[22:23], v[30:31], v[36:37] op_sel_hi:[1,0]
	v_cvt_pk_bf16_f32 v19, v20, v21
	global_store_dwordx2 v[34:35], v[18:19], off offset:32
	v_mov_b32_e32 v18, v212
	v_mov_b32_e32 v19, v213
	v_mov_b32_e32 v20, v214
	v_mov_b32_e32 v21, v215
	v_pk_mul_f32 v[18:19], v[22:23], v[18:19]
	v_pk_mul_f32 v[22:23], v[28:29], v[36:37] op_sel_hi:[1,0]
	v_cvt_pk_bf16_f32 v18, v18, v19
	v_pk_mul_f32 v[20:21], v[22:23], v[20:21]
	v_pk_mul_f32 v[22:23], v[32:33], v[36:37] op_sel_hi:[1,0]
	v_cvt_pk_bf16_f32 v19, v20, v21
	global_store_dwordx2 v[34:35], v[18:19], off offset:48
	v_mov_b32_e32 v18, v222
	v_mov_b32_e32 v19, v223
	v_mov_b32_e32 v20, v224
	v_mov_b32_e32 v21, v225
	v_pk_mul_f32 v[18:19], v[22:23], v[18:19]
	v_pk_mul_f32 v[2:3], v[2:3], v[20:21]
	v_cvt_pk_bf16_f32 v18, v18, v19
	v_cvt_pk_bf16_f32 v19, v2, v3
	global_store_dwordx2 v[34:35], v[18:19], off offset:64
	v_pk_mul_f32 v[2:3], v[6:7], v[36:37] op_sel_hi:[1,0]
	v_pk_mul_f32 v[6:7], v[10:11], v[36:37] op_sel_hi:[1,0]
	v_mov_b32_e32 v18, v226
	v_mov_b32_e32 v19, v227
	v_mov_b32_e32 v20, v228
	v_mov_b32_e32 v21, v229
	v_pk_mul_f32 v[2:3], v[2:3], v[18:19]
	v_pk_mul_f32 v[4:5], v[4:5], v[20:21]
	v_cvt_pk_bf16_f32 v2, v2, v3
	v_cvt_pk_bf16_f32 v3, v4, v5
	global_store_dwordx2 v[34:35], v[2:3], off offset:80
	v_mov_b32_e32 v2, v130
	v_mov_b32_e32 v3, v131
	v_mov_b32_e32 v4, v132
	v_mov_b32_e32 v5, v133
	v_pk_mul_f32 v[2:3], v[6:7], v[2:3]
	v_pk_mul_f32 v[6:7], v[8:9], v[36:37] op_sel_hi:[1,0]
	v_cvt_pk_bf16_f32 v2, v2, v3
	v_pk_mul_f32 v[4:5], v[6:7], v[4:5]
	v_pk_mul_f32 v[6:7], v[12:13], v[36:37] op_sel_hi:[1,0]
	v_cvt_pk_bf16_f32 v3, v4, v5
	global_store_dwordx2 v[34:35], v[2:3], off offset:96
	v_mov_b32_e32 v2, v134
	v_mov_b32_e32 v3, v135
	v_mov_b32_e32 v4, v136
	v_mov_b32_e32 v5, v137
	v_pk_mul_f32 v[2:3], v[6:7], v[2:3]
	v_pk_mul_f32 v[6:7], v[14:15], v[36:37] op_sel_hi:[1,0]
	v_cvt_pk_bf16_f32 v2, v2, v3
	v_pk_mul_f32 v[4:5], v[6:7], v[4:5]
	s_nop 0
	v_cvt_pk_bf16_f32 v3, v4, v5
	global_store_dwordx2 v[34:35], v[2:3], off offset:112
	s_branch .LBB0_34
